# all 1404 W_up transposes tiles moved to the CUs idle in the last GEMM1 round; P4 transposes only W_down
# baseline (speedup 1.0000x reference)
.LBB0_17:
	s_waitcnt lgkmcnt(0)
	v_writelane_b32 v237, s16, 28
	s_lshr_b32 s33, s10, 6
	s_cmp_lt_i32 s94, 1
	v_writelane_b32 v237, s17, 29
	v_writelane_b32 v237, s18, 30
	v_writelane_b32 v237, s19, 31
	v_writelane_b32 v237, s20, 32
	v_writelane_b32 v237, s21, 33
	v_writelane_b32 v237, s22, 34
	v_writelane_b32 v237, s23, 35
	v_writelane_b32 v237, s24, 36
	v_writelane_b32 v237, s25, 37
	v_writelane_b32 v237, s26, 38
	v_writelane_b32 v237, s27, 39
	v_writelane_b32 v237, s28, 40
	v_writelane_b32 v237, s29, 41
	v_writelane_b32 v237, s30, 42
	v_writelane_b32 v237, s31, 43
	s_load_dwordx16 s[36:51], s[0:1], 0x40
	s_load_dwordx16 s[12:27], s[0:1], 0x80
	s_cselect_b64 s[0:1], -1, 0
	s_cmp_gt_i32 s95, 0
	s_cselect_b64 s[2:3], -1, 0
	s_and_b64 s[68:69], s[0:1], s[2:3]
	s_waitcnt lgkmcnt(0)
	v_writelane_b32 v237, s12, 44
	s_andn2_b64 vcc, exec, s[68:69]
	v_and_b32_e32 v128, 63, v172
	v_writelane_b32 v237, s13, 45
	v_writelane_b32 v237, s14, 46
	v_writelane_b32 v237, s15, 47
	v_writelane_b32 v237, s16, 48
	v_writelane_b32 v237, s17, 49
	v_writelane_b32 v237, s18, 50
	v_writelane_b32 v237, s19, 51
	v_writelane_b32 v237, s20, 52
	v_writelane_b32 v237, s21, 53
	v_writelane_b32 v237, s22, 54
	v_writelane_b32 v237, s23, 55
	v_writelane_b32 v237, s24, 56
	v_writelane_b32 v237, s25, 57
	v_writelane_b32 v237, s26, 58
	v_writelane_b32 v237, s27, 59
	s_cbranch_vccnz .LBB0_147
	s_cmpk_eq_i32 s96, 0x100
	s_movk_i32 s0, 0x5d4
	s_cselect_b32 s53, s0, 0xe10
	s_cmp_lt_i32 s76, s53
	v_mov_b32_e32 v35, v172
	s_cselect_b64 s[4:5], -1, 0
	s_and_b64 vcc, exec, s[4:5]
	v_ashrrev_i32_e32 v32, 5, v35
	v_lshlrev_b32_e32 v0, 2, v35
	s_cbranch_vccnz .LBB0_21
	v_ashrrev_i32_e32 v33, 5, v35
	v_and_b32_e32 v39, 0x7c, v0
	s_lshl_b32 s52, s76, 3
	s_cbranch_execz .LBB0_22
	v_mov_b32_e32 v31, 0
	v_mov_b32_e32 v30, v31
	v_mov_b32_e32 v29, v31
	v_mov_b32_e32 v28, v31
	v_mov_b32_e32 v27, v31
	v_mov_b32_e32 v26, v31
	v_mov_b32_e32 v25, v31
	v_mov_b32_e32 v24, v31
	v_mov_b32_e32 v23, v31
	v_mov_b32_e32 v22, v31
	v_mov_b32_e32 v21, v31
	v_mov_b32_e32 v20, v31
	v_mov_b32_e32 v19, v31
	v_mov_b32_e32 v18, v31
	v_mov_b32_e32 v17, v31
	v_mov_b32_e32 v16, v31
	v_mov_b32_e32 v15, v31
	v_mov_b32_e32 v14, v31
	v_mov_b32_e32 v13, v31
	v_mov_b32_e32 v12, v31
	v_mov_b32_e32 v11, v31
	v_mov_b32_e32 v10, v31
	v_mov_b32_e32 v9, v31
	v_mov_b32_e32 v8, v31
	v_mov_b32_e32 v7, v31
	v_mov_b32_e32 v6, v31
	v_mov_b32_e32 v5, v31
	v_mov_b32_e32 v4, v31
	v_mov_b32_e32 v3, v31
	v_mov_b32_e32 v2, v31
	v_mov_b32_e32 v1, v31
	v_mov_b32_e32 v0, v31
	v_mov_b32_e32 v32, v33
	s_andn2_b64 vcc, exec, s[4:5]
	s_cbranch_vccz .LBB0_72
	s_branch .LBB0_121

.LBB0_268:
	s_cmpk_lg_i32 s96, 0x100
	s_cbranch_scc1 .Ltup_skip
	s_cmpk_lt_u32 s76, 0x7b
	s_cbranch_scc1 .Ltup_skip
	s_cmpk_gt_u32 s76, 0xef
	s_cbranch_scc1 .Ltup_skip
	v_readlane_b32 s2, v237, 42
	v_readlane_b32 s3, v237, 43
	v_readlane_b32 s4, v237, 40
	v_readlane_b32 s5, v237, 41
	s_add_u32 s40, s92, 0x3000000
	s_addc_u32 s41, s93, 0
	v_and_b32_e32 v83, 31, v172
	v_lshrrev_b32_e32 v84, 5, v172
	v_mul_u32_u24_e32 v66, 0x58000, v84
	v_lshl_add_u32 v66, v83, 4, v66
	v_add_u32_e32 v67, 0xb000, v66
	v_add_u32_e32 v68, 0x16000, v66
	v_add_u32_e32 v69, 0x21000, v66
	v_add_u32_e32 v70, 0x2c000, v66
	v_add_u32_e32 v71, 0x37000, v66
	v_add_u32_e32 v72, 0x42000, v66
	v_add_u32_e32 v73, 0x4d000, v66
	v_lshlrev_b32_e32 v74, 5, v84
	v_and_b32_e32 v85, 15, v83
	v_xor_b32_e32 v85, v85, v84
	v_lshlrev_b32_e32 v85, 4, v85
	v_lshl_add_u32 v75, v83, 10, v85
	v_lshrrev_b32_e32 v83, 4, v172
	v_and_b32_e32 v84, 15, v172
	v_lshrrev_b32_e32 v85, 6, v172
	v_xor_b32_e32 v85, v85, v84
	v_lshlrev_b32_e32 v85, 4, v85
	v_lshl_add_u32 v76, v83, 8, v85
	v_xor_b32_e32 v77, 0x80, v76
	v_lshlrev_b32_e32 v84, 4, v84
	v_lshl_add_u32 v79, v83, 12, v84
	v_add_u32_e32 v80, 0x20000, v79
	v_add_u32_e32 v81, 0x40000, v79
	v_add_u32_e32 v82, 0x60000, v79
	s_add_i32 s9, s76, 0xffffff89
	s_mul_i32 s12, s9, 0xba2f
	s_lshr_b32 s12, s12, 22
	s_mul_i32 s57, s12, 0x58
	s_sub_i32 s42, s9, s57
	s_mul_i32 s57, s12, 0x580000
	s_lshl_b32 s58, s42, 9
	s_add_i32 s57, s57, s58
	s_add_u32 s52, s2, s57
	s_addc_u32 s53, s3, 0
	s_lshl_b32 s58, s12, 9
	s_add_u32 s54, s4, s58
	s_addc_u32 s55, s5, 0
	s_cmp_gt_u32 s42, 43
	s_cselect_b32 s58, 0x80000, 0
	s_cselect_b32 s57, 44, 0
	s_sub_i32 s57, s42, s57
	s_lshl_b32 s57, s57, 20
	s_add_i32 s57, s57, s58
	s_lshl_b32 s58, s12, 8
	s_add_i32 s57, s57, s58
	s_add_u32 s60, s40, s57
	s_addc_u32 s61, s41, 0
	s_add_i32 s9, s9, 0x75
	s_nop 0
	global_load_dwordx4 v[206:209], v74, s[54:55] offset:0
	global_load_dwordx4 v[210:213], v74, s[54:55] offset:16
	global_load_dwordx4 v[174:177], v66, s[52:53]
	global_load_dwordx4 v[178:181], v67, s[52:53]
	global_load_dwordx4 v[182:185], v68, s[52:53]
	global_load_dwordx4 v[186:189], v69, s[52:53]
	global_load_dwordx4 v[190:193], v70, s[52:53]
	global_load_dwordx4 v[194:197], v71, s[52:53]
	global_load_dwordx4 v[198:201], v72, s[52:53]
	global_load_dwordx4 v[202:205], v73, s[52:53]
	s_mul_i32 s12, s9, 0xba2f
	s_lshr_b32 s12, s12, 22
	s_mul_i32 s57, s12, 0x58
	s_sub_i32 s42, s9, s57
	s_mul_i32 s57, s12, 0x580000
	s_lshl_b32 s58, s42, 9
	s_add_i32 s57, s57, s58
	s_add_u32 s62, s2, s57
	s_addc_u32 s63, s3, 0
	s_lshl_b32 s58, s12, 9
	s_add_u32 s64, s4, s58
	s_addc_u32 s65, s5, 0
	s_cmp_gt_u32 s42, 43
	s_cselect_b32 s58, 0x80000, 0
	s_cselect_b32 s57, 44, 0
	s_sub_i32 s57, s42, s57
	s_lshl_b32 s57, s57, 20
	s_add_i32 s57, s57, s58
	s_lshl_b32 s58, s12, 8
	s_add_i32 s57, s57, s58
	s_add_u32 s66, s40, s57
	s_addc_u32 s67, s41, 0
	s_add_i32 s9, s9, 0x75
	s_nop 0
	global_load_dwordx4 v[162:165], v74, s[64:65] offset:0
	global_load_dwordx4 v[166:169], v74, s[64:65] offset:16
	global_load_dwordx4 v[130:133], v66, s[62:63]
	global_load_dwordx4 v[134:137], v67, s[62:63]
	global_load_dwordx4 v[138:141], v68, s[62:63]
	global_load_dwordx4 v[142:145], v69, s[62:63]
	global_load_dwordx4 v[146:149], v70, s[62:63]
	global_load_dwordx4 v[150:153], v71, s[62:63]
	global_load_dwordx4 v[154:157], v72, s[62:63]
	global_load_dwordx4 v[158:161], v73, s[62:63]
	s_waitcnt vmcnt(10)
	v_mul_f32_e32 v174, v174, v206
	v_mul_f32_e32 v175, v175, v206
	v_mul_f32_e32 v176, v176, v206
	v_mul_f32_e32 v177, v177, v206
	v_mul_f32_e32 v178, v178, v207
	v_mul_f32_e32 v179, v179, v207
	v_mul_f32_e32 v180, v180, v207
	v_mul_f32_e32 v181, v181, v207
	v_mul_f32_e32 v182, v182, v208
	v_mul_f32_e32 v183, v183, v208
	v_mul_f32_e32 v184, v184, v208
	v_mul_f32_e32 v185, v185, v208
	v_mul_f32_e32 v186, v186, v209
	v_mul_f32_e32 v187, v187, v209
	v_mul_f32_e32 v188, v188, v209
	v_mul_f32_e32 v189, v189, v209
	v_mul_f32_e32 v190, v190, v210
	v_mul_f32_e32 v191, v191, v210
	v_mul_f32_e32 v192, v192, v210
	v_mul_f32_e32 v193, v193, v210
	v_mul_f32_e32 v194, v194, v211
	v_mul_f32_e32 v195, v195, v211
	v_mul_f32_e32 v196, v196, v211
	v_mul_f32_e32 v197, v197, v211
	v_mul_f32_e32 v198, v198, v212
	v_mul_f32_e32 v199, v199, v212
	v_mul_f32_e32 v200, v200, v212
	v_mul_f32_e32 v201, v201, v212
	v_mul_f32_e32 v202, v202, v213
	v_mul_f32_e32 v203, v203, v213
	v_mul_f32_e32 v204, v204, v213
	v_mul_f32_e32 v205, v205, v213
	v_cvt_pk_bf16_f32 v214, v174, v178
	v_cvt_pk_bf16_f32 v215, v182, v186
	v_cvt_pk_bf16_f32 v216, v190, v194
	v_cvt_pk_bf16_f32 v217, v198, v202
	v_cvt_pk_bf16_f32 v218, v175, v179
	v_cvt_pk_bf16_f32 v219, v183, v187
	v_cvt_pk_bf16_f32 v220, v191, v195
	v_cvt_pk_bf16_f32 v221, v199, v203
	v_cvt_pk_bf16_f32 v222, v176, v180
	v_cvt_pk_bf16_f32 v223, v184, v188
	v_cvt_pk_bf16_f32 v224, v192, v196
	v_cvt_pk_bf16_f32 v225, v200, v204
	v_cvt_pk_bf16_f32 v226, v177, v181
	v_cvt_pk_bf16_f32 v227, v185, v189
	v_cvt_pk_bf16_f32 v228, v193, v197
	v_cvt_pk_bf16_f32 v229, v201, v205
	ds_write_b128 v75, v[214:217] offset:0
	ds_write_b128 v75, v[218:221] offset:256
	ds_write_b128 v75, v[222:225] offset:512
	ds_write_b128 v75, v[226:229] offset:768
	s_mov_b64 s[68:69], s[60:61]
	s_mul_i32 s12, s9, 0xba2f
	s_lshr_b32 s12, s12, 22
	s_mul_i32 s57, s12, 0x58
	s_sub_i32 s42, s9, s57
	s_mul_i32 s57, s12, 0x580000
	s_lshl_b32 s58, s42, 9
	s_add_i32 s57, s57, s58
	s_add_u32 s52, s2, s57
	s_addc_u32 s53, s3, 0
	s_lshl_b32 s58, s12, 9
	s_add_u32 s54, s4, s58
	s_addc_u32 s55, s5, 0
	s_cmp_gt_u32 s42, 43
	s_cselect_b32 s58, 0x80000, 0
	s_cselect_b32 s57, 44, 0
	s_sub_i32 s57, s42, s57
	s_lshl_b32 s57, s57, 20
	s_add_i32 s57, s57, s58
	s_lshl_b32 s58, s12, 8
	s_add_i32 s57, s57, s58
	s_add_u32 s60, s40, s57
	s_addc_u32 s61, s41, 0
	s_add_i32 s9, s9, 0x75
	s_nop 0
	global_load_dwordx4 v[206:209], v74, s[54:55] offset:0
	global_load_dwordx4 v[210:213], v74, s[54:55] offset:16
	global_load_dwordx4 v[174:177], v66, s[52:53]
	global_load_dwordx4 v[178:181], v67, s[52:53]
	global_load_dwordx4 v[182:185], v68, s[52:53]
	global_load_dwordx4 v[186:189], v69, s[52:53]
	global_load_dwordx4 v[190:193], v70, s[52:53]
	global_load_dwordx4 v[194:197], v71, s[52:53]
	global_load_dwordx4 v[198:201], v72, s[52:53]
	global_load_dwordx4 v[202:205], v73, s[52:53]
	s_waitcnt lgkmcnt(0)
	s_barrier
	ds_read_b128 v[50:53], v76 offset:0
	ds_read_b128 v[54:57], v77 offset:8192
	ds_read_b128 v[58:61], v76 offset:16384
	ds_read_b128 v[62:65], v77 offset:24576
	s_waitcnt lgkmcnt(3)
	global_store_dwordx4 v79, v[50:53], s[68:69]
	s_waitcnt lgkmcnt(2)
	global_store_dwordx4 v80, v[54:57], s[68:69]
	s_waitcnt lgkmcnt(1)
	global_store_dwordx4 v81, v[58:61], s[68:69]
	s_waitcnt lgkmcnt(0)
	global_store_dwordx4 v82, v[62:65], s[68:69]
	s_waitcnt vmcnt(14)
	v_mul_f32_e32 v130, v130, v162
	v_mul_f32_e32 v131, v131, v162
	v_mul_f32_e32 v132, v132, v162
	v_mul_f32_e32 v133, v133, v162
	v_mul_f32_e32 v134, v134, v163
	v_mul_f32_e32 v135, v135, v163
	v_mul_f32_e32 v136, v136, v163
	v_mul_f32_e32 v137, v137, v163
	v_mul_f32_e32 v138, v138, v164
	v_mul_f32_e32 v139, v139, v164
	v_mul_f32_e32 v140, v140, v164
	v_mul_f32_e32 v141, v141, v164
	v_mul_f32_e32 v142, v142, v165
	v_mul_f32_e32 v143, v143, v165
	v_mul_f32_e32 v144, v144, v165
	v_mul_f32_e32 v145, v145, v165
	v_mul_f32_e32 v146, v146, v166
	v_mul_f32_e32 v147, v147, v166
	v_mul_f32_e32 v148, v148, v166
	v_mul_f32_e32 v149, v149, v166
	v_mul_f32_e32 v150, v150, v167
	v_mul_f32_e32 v151, v151, v167
	v_mul_f32_e32 v152, v152, v167
	v_mul_f32_e32 v153, v153, v167
	v_mul_f32_e32 v154, v154, v168
	v_mul_f32_e32 v155, v155, v168
	v_mul_f32_e32 v156, v156, v168
	v_mul_f32_e32 v157, v157, v168
	v_mul_f32_e32 v158, v158, v169
	v_mul_f32_e32 v159, v159, v169
	v_mul_f32_e32 v160, v160, v169
	v_mul_f32_e32 v161, v161, v169
	v_cvt_pk_bf16_f32 v214, v130, v134
	v_cvt_pk_bf16_f32 v215, v138, v142
	v_cvt_pk_bf16_f32 v216, v146, v150
	v_cvt_pk_bf16_f32 v217, v154, v158
	v_cvt_pk_bf16_f32 v218, v131, v135
	v_cvt_pk_bf16_f32 v219, v139, v143
	v_cvt_pk_bf16_f32 v220, v147, v151
	v_cvt_pk_bf16_f32 v221, v155, v159
	v_cvt_pk_bf16_f32 v222, v132, v136
	v_cvt_pk_bf16_f32 v223, v140, v144
	v_cvt_pk_bf16_f32 v224, v148, v152
	v_cvt_pk_bf16_f32 v225, v156, v160
	v_cvt_pk_bf16_f32 v226, v133, v137
	v_cvt_pk_bf16_f32 v227, v141, v145
	v_cvt_pk_bf16_f32 v228, v149, v153
	v_cvt_pk_bf16_f32 v229, v157, v161
	ds_write_b128 v75, v[214:217] offset:32768
	ds_write_b128 v75, v[218:221] offset:33024
	ds_write_b128 v75, v[222:225] offset:33280
	ds_write_b128 v75, v[226:229] offset:33536
	s_mov_b64 s[70:71], s[66:67]
	s_mul_i32 s12, s9, 0xba2f
	s_lshr_b32 s12, s12, 22
	s_mul_i32 s57, s12, 0x58
	s_sub_i32 s42, s9, s57
	s_mul_i32 s57, s12, 0x580000
	s_lshl_b32 s58, s42, 9
	s_add_i32 s57, s57, s58
	s_add_u32 s62, s2, s57
	s_addc_u32 s63, s3, 0
	s_lshl_b32 s58, s12, 9
	s_add_u32 s64, s4, s58
	s_addc_u32 s65, s5, 0
	s_cmp_gt_u32 s42, 43
	s_cselect_b32 s58, 0x80000, 0
	s_cselect_b32 s57, 44, 0
	s_sub_i32 s57, s42, s57
	s_lshl_b32 s57, s57, 20
	s_add_i32 s57, s57, s58
	s_lshl_b32 s58, s12, 8
	s_add_i32 s57, s57, s58
	s_add_u32 s66, s40, s57
	s_addc_u32 s67, s41, 0
	s_add_i32 s9, s9, 0x75
	s_nop 0
	global_load_dwordx4 v[162:165], v74, s[64:65] offset:0
	global_load_dwordx4 v[166:169], v74, s[64:65] offset:16
	global_load_dwordx4 v[130:133], v66, s[62:63]
	global_load_dwordx4 v[134:137], v67, s[62:63]
	global_load_dwordx4 v[138:141], v68, s[62:63]
	global_load_dwordx4 v[142:145], v69, s[62:63]
	global_load_dwordx4 v[146:149], v70, s[62:63]
	global_load_dwordx4 v[150:153], v71, s[62:63]
	global_load_dwordx4 v[154:157], v72, s[62:63]
	global_load_dwordx4 v[158:161], v73, s[62:63]
	s_waitcnt lgkmcnt(0)
	s_barrier
	ds_read_b128 v[102:105], v76 offset:32768
	ds_read_b128 v[106:109], v77 offset:40960
	ds_read_b128 v[110:113], v76 offset:49152
	ds_read_b128 v[114:117], v77 offset:57344
	s_waitcnt lgkmcnt(3)
	global_store_dwordx4 v79, v[102:105], s[70:71]
	s_waitcnt lgkmcnt(2)
	global_store_dwordx4 v80, v[106:109], s[70:71]
	s_waitcnt lgkmcnt(1)
	global_store_dwordx4 v81, v[110:113], s[70:71]
	s_waitcnt lgkmcnt(0)
	global_store_dwordx4 v82, v[114:117], s[70:71]
	s_waitcnt vmcnt(18)
	v_mul_f32_e32 v174, v174, v206
	v_mul_f32_e32 v175, v175, v206
	v_mul_f32_e32 v176, v176, v206
	v_mul_f32_e32 v177, v177, v206
	v_mul_f32_e32 v178, v178, v207
	v_mul_f32_e32 v179, v179, v207
	v_mul_f32_e32 v180, v180, v207
	v_mul_f32_e32 v181, v181, v207
	v_mul_f32_e32 v182, v182, v208
	v_mul_f32_e32 v183, v183, v208
	v_mul_f32_e32 v184, v184, v208
	v_mul_f32_e32 v185, v185, v208
	v_mul_f32_e32 v186, v186, v209
	v_mul_f32_e32 v187, v187, v209
	v_mul_f32_e32 v188, v188, v209
	v_mul_f32_e32 v189, v189, v209
	v_mul_f32_e32 v190, v190, v210
	v_mul_f32_e32 v191, v191, v210
	v_mul_f32_e32 v192, v192, v210
	v_mul_f32_e32 v193, v193, v210
	v_mul_f32_e32 v194, v194, v211
	v_mul_f32_e32 v195, v195, v211
	v_mul_f32_e32 v196, v196, v211
	v_mul_f32_e32 v197, v197, v211
	v_mul_f32_e32 v198, v198, v212
	v_mul_f32_e32 v199, v199, v212
	v_mul_f32_e32 v200, v200, v212
	v_mul_f32_e32 v201, v201, v212
	v_mul_f32_e32 v202, v202, v213
	v_mul_f32_e32 v203, v203, v213
	v_mul_f32_e32 v204, v204, v213
	v_mul_f32_e32 v205, v205, v213
	v_cvt_pk_bf16_f32 v214, v174, v178
	v_cvt_pk_bf16_f32 v215, v182, v186
	v_cvt_pk_bf16_f32 v216, v190, v194
	v_cvt_pk_bf16_f32 v217, v198, v202
	v_cvt_pk_bf16_f32 v218, v175, v179
	v_cvt_pk_bf16_f32 v219, v183, v187
	v_cvt_pk_bf16_f32 v220, v191, v195
	v_cvt_pk_bf16_f32 v221, v199, v203
	v_cvt_pk_bf16_f32 v222, v176, v180
	v_cvt_pk_bf16_f32 v223, v184, v188
	v_cvt_pk_bf16_f32 v224, v192, v196
	v_cvt_pk_bf16_f32 v225, v200, v204
	v_cvt_pk_bf16_f32 v226, v177, v181
	v_cvt_pk_bf16_f32 v227, v185, v189
	v_cvt_pk_bf16_f32 v228, v193, v197
	v_cvt_pk_bf16_f32 v229, v201, v205
	ds_write_b128 v75, v[214:217] offset:0
	ds_write_b128 v75, v[218:221] offset:256
	ds_write_b128 v75, v[222:225] offset:512
	ds_write_b128 v75, v[226:229] offset:768
	s_mov_b64 s[68:69], s[60:61]
	s_mul_i32 s12, s9, 0xba2f
	s_lshr_b32 s12, s12, 22
	s_mul_i32 s57, s12, 0x58
	s_sub_i32 s42, s9, s57
	s_mul_i32 s57, s12, 0x580000
	s_lshl_b32 s58, s42, 9
	s_add_i32 s57, s57, s58
	s_add_u32 s52, s2, s57
	s_addc_u32 s53, s3, 0
	s_lshl_b32 s58, s12, 9
	s_add_u32 s54, s4, s58
	s_addc_u32 s55, s5, 0
	s_cmp_gt_u32 s42, 43
	s_cselect_b32 s58, 0x80000, 0
	s_cselect_b32 s57, 44, 0
	s_sub_i32 s57, s42, s57
	s_lshl_b32 s57, s57, 20
	s_add_i32 s57, s57, s58
	s_lshl_b32 s58, s12, 8
	s_add_i32 s57, s57, s58
	s_add_u32 s60, s40, s57
	s_addc_u32 s61, s41, 0
	s_add_i32 s9, s9, 0x75
	s_nop 0
	global_load_dwordx4 v[206:209], v74, s[54:55] offset:0
	global_load_dwordx4 v[210:213], v74, s[54:55] offset:16
	global_load_dwordx4 v[174:177], v66, s[52:53]
	global_load_dwordx4 v[178:181], v67, s[52:53]
	global_load_dwordx4 v[182:185], v68, s[52:53]
	global_load_dwordx4 v[186:189], v69, s[52:53]
	global_load_dwordx4 v[190:193], v70, s[52:53]
	global_load_dwordx4 v[194:197], v71, s[52:53]
	global_load_dwordx4 v[198:201], v72, s[52:53]
	global_load_dwordx4 v[202:205], v73, s[52:53]
	s_waitcnt lgkmcnt(0)
	s_barrier
	ds_read_b128 v[50:53], v76 offset:0
	ds_read_b128 v[54:57], v77 offset:8192
	ds_read_b128 v[58:61], v76 offset:16384
	ds_read_b128 v[62:65], v77 offset:24576
	s_waitcnt lgkmcnt(3)
	global_store_dwordx4 v79, v[50:53], s[68:69]
	s_waitcnt lgkmcnt(2)
	global_store_dwordx4 v80, v[54:57], s[68:69]
	s_waitcnt lgkmcnt(1)
	global_store_dwordx4 v81, v[58:61], s[68:69]
	s_waitcnt lgkmcnt(0)
	global_store_dwordx4 v82, v[62:65], s[68:69]
	s_waitcnt vmcnt(18)
	v_mul_f32_e32 v130, v130, v162
	v_mul_f32_e32 v131, v131, v162
	v_mul_f32_e32 v132, v132, v162
	v_mul_f32_e32 v133, v133, v162
	v_mul_f32_e32 v134, v134, v163
	v_mul_f32_e32 v135, v135, v163
	v_mul_f32_e32 v136, v136, v163
	v_mul_f32_e32 v137, v137, v163
	v_mul_f32_e32 v138, v138, v164
	v_mul_f32_e32 v139, v139, v164
	v_mul_f32_e32 v140, v140, v164
	v_mul_f32_e32 v141, v141, v164
	v_mul_f32_e32 v142, v142, v165
	v_mul_f32_e32 v143, v143, v165
	v_mul_f32_e32 v144, v144, v165
	v_mul_f32_e32 v145, v145, v165
	v_mul_f32_e32 v146, v146, v166
	v_mul_f32_e32 v147, v147, v166
	v_mul_f32_e32 v148, v148, v166
	v_mul_f32_e32 v149, v149, v166
	v_mul_f32_e32 v150, v150, v167
	v_mul_f32_e32 v151, v151, v167
	v_mul_f32_e32 v152, v152, v167
	v_mul_f32_e32 v153, v153, v167
	v_mul_f32_e32 v154, v154, v168
	v_mul_f32_e32 v155, v155, v168
	v_mul_f32_e32 v156, v156, v168
	v_mul_f32_e32 v157, v157, v168
	v_mul_f32_e32 v158, v158, v169
	v_mul_f32_e32 v159, v159, v169
	v_mul_f32_e32 v160, v160, v169
	v_mul_f32_e32 v161, v161, v169
	v_cvt_pk_bf16_f32 v214, v130, v134
	v_cvt_pk_bf16_f32 v215, v138, v142
	v_cvt_pk_bf16_f32 v216, v146, v150
	v_cvt_pk_bf16_f32 v217, v154, v158
	v_cvt_pk_bf16_f32 v218, v131, v135
	v_cvt_pk_bf16_f32 v219, v139, v143
	v_cvt_pk_bf16_f32 v220, v147, v151
	v_cvt_pk_bf16_f32 v221, v155, v159
	v_cvt_pk_bf16_f32 v222, v132, v136
	v_cvt_pk_bf16_f32 v223, v140, v144
	v_cvt_pk_bf16_f32 v224, v148, v152
	v_cvt_pk_bf16_f32 v225, v156, v160
	v_cvt_pk_bf16_f32 v226, v133, v137
	v_cvt_pk_bf16_f32 v227, v141, v145
	v_cvt_pk_bf16_f32 v228, v149, v153
	v_cvt_pk_bf16_f32 v229, v157, v161
	ds_write_b128 v75, v[214:217] offset:32768
	ds_write_b128 v75, v[218:221] offset:33024
	ds_write_b128 v75, v[222:225] offset:33280
	ds_write_b128 v75, v[226:229] offset:33536
	s_mov_b64 s[70:71], s[66:67]
	s_mul_i32 s12, s9, 0xba2f
	s_lshr_b32 s12, s12, 22
	s_mul_i32 s57, s12, 0x58
	s_sub_i32 s42, s9, s57
	s_mul_i32 s57, s12, 0x580000
	s_lshl_b32 s58, s42, 9
	s_add_i32 s57, s57, s58
	s_add_u32 s62, s2, s57
	s_addc_u32 s63, s3, 0
	s_lshl_b32 s58, s12, 9
	s_add_u32 s64, s4, s58
	s_addc_u32 s65, s5, 0
	s_cmp_gt_u32 s42, 43
	s_cselect_b32 s58, 0x80000, 0
	s_cselect_b32 s57, 44, 0
	s_sub_i32 s57, s42, s57
	s_lshl_b32 s57, s57, 20
	s_add_i32 s57, s57, s58
	s_lshl_b32 s58, s12, 8
	s_add_i32 s57, s57, s58
	s_add_u32 s66, s40, s57
	s_addc_u32 s67, s41, 0
	s_add_i32 s9, s9, 0x75
	s_nop 0
	global_load_dwordx4 v[162:165], v74, s[64:65] offset:0
	global_load_dwordx4 v[166:169], v74, s[64:65] offset:16
	global_load_dwordx4 v[130:133], v66, s[62:63]
	global_load_dwordx4 v[134:137], v67, s[62:63]
	global_load_dwordx4 v[138:141], v68, s[62:63]
	global_load_dwordx4 v[142:145], v69, s[62:63]
	global_load_dwordx4 v[146:149], v70, s[62:63]
	global_load_dwordx4 v[150:153], v71, s[62:63]
	global_load_dwordx4 v[154:157], v72, s[62:63]
	global_load_dwordx4 v[158:161], v73, s[62:63]
	s_waitcnt lgkmcnt(0)
	s_barrier
	ds_read_b128 v[102:105], v76 offset:32768
	ds_read_b128 v[106:109], v77 offset:40960
	ds_read_b128 v[110:113], v76 offset:49152
	ds_read_b128 v[114:117], v77 offset:57344
	s_waitcnt lgkmcnt(3)
	global_store_dwordx4 v79, v[102:105], s[70:71]
	s_waitcnt lgkmcnt(2)
	global_store_dwordx4 v80, v[106:109], s[70:71]
	s_waitcnt lgkmcnt(1)
	global_store_dwordx4 v81, v[110:113], s[70:71]
	s_waitcnt lgkmcnt(0)
	global_store_dwordx4 v82, v[114:117], s[70:71]
	s_waitcnt vmcnt(18)
	v_mul_f32_e32 v174, v174, v206
	v_mul_f32_e32 v175, v175, v206
	v_mul_f32_e32 v176, v176, v206
	v_mul_f32_e32 v177, v177, v206
	v_mul_f32_e32 v178, v178, v207
	v_mul_f32_e32 v179, v179, v207
	v_mul_f32_e32 v180, v180, v207
	v_mul_f32_e32 v181, v181, v207
	v_mul_f32_e32 v182, v182, v208
	v_mul_f32_e32 v183, v183, v208
	v_mul_f32_e32 v184, v184, v208
	v_mul_f32_e32 v185, v185, v208
	v_mul_f32_e32 v186, v186, v209
	v_mul_f32_e32 v187, v187, v209
	v_mul_f32_e32 v188, v188, v209
	v_mul_f32_e32 v189, v189, v209
	v_mul_f32_e32 v190, v190, v210
	v_mul_f32_e32 v191, v191, v210
	v_mul_f32_e32 v192, v192, v210
	v_mul_f32_e32 v193, v193, v210
	v_mul_f32_e32 v194, v194, v211
	v_mul_f32_e32 v195, v195, v211
	v_mul_f32_e32 v196, v196, v211
	v_mul_f32_e32 v197, v197, v211
	v_mul_f32_e32 v198, v198, v212
	v_mul_f32_e32 v199, v199, v212
	v_mul_f32_e32 v200, v200, v212
	v_mul_f32_e32 v201, v201, v212
	v_mul_f32_e32 v202, v202, v213
	v_mul_f32_e32 v203, v203, v213
	v_mul_f32_e32 v204, v204, v213
	v_mul_f32_e32 v205, v205, v213
	v_cvt_pk_bf16_f32 v214, v174, v178
	v_cvt_pk_bf16_f32 v215, v182, v186
	v_cvt_pk_bf16_f32 v216, v190, v194
	v_cvt_pk_bf16_f32 v217, v198, v202
	v_cvt_pk_bf16_f32 v218, v175, v179
	v_cvt_pk_bf16_f32 v219, v183, v187
	v_cvt_pk_bf16_f32 v220, v191, v195
	v_cvt_pk_bf16_f32 v221, v199, v203
	v_cvt_pk_bf16_f32 v222, v176, v180
	v_cvt_pk_bf16_f32 v223, v184, v188
	v_cvt_pk_bf16_f32 v224, v192, v196
	v_cvt_pk_bf16_f32 v225, v200, v204
	v_cvt_pk_bf16_f32 v226, v177, v181
	v_cvt_pk_bf16_f32 v227, v185, v189
	v_cvt_pk_bf16_f32 v228, v193, v197
	v_cvt_pk_bf16_f32 v229, v201, v205
	ds_write_b128 v75, v[214:217] offset:0
	ds_write_b128 v75, v[218:221] offset:256
	ds_write_b128 v75, v[222:225] offset:512
	ds_write_b128 v75, v[226:229] offset:768
	s_mov_b64 s[68:69], s[60:61]
	s_mul_i32 s12, s9, 0xba2f
	s_lshr_b32 s12, s12, 22
	s_mul_i32 s57, s12, 0x58
	s_sub_i32 s42, s9, s57
	s_mul_i32 s57, s12, 0x580000
	s_lshl_b32 s58, s42, 9
	s_add_i32 s57, s57, s58
	s_add_u32 s52, s2, s57
	s_addc_u32 s53, s3, 0
	s_lshl_b32 s58, s12, 9
	s_add_u32 s54, s4, s58
	s_addc_u32 s55, s5, 0
	s_cmp_gt_u32 s42, 43
	s_cselect_b32 s58, 0x80000, 0
	s_cselect_b32 s57, 44, 0
	s_sub_i32 s57, s42, s57
	s_lshl_b32 s57, s57, 20
	s_add_i32 s57, s57, s58
	s_lshl_b32 s58, s12, 8
	s_add_i32 s57, s57, s58
	s_add_u32 s60, s40, s57
	s_addc_u32 s61, s41, 0
	s_add_i32 s9, s9, 0x75
	s_nop 0
	global_load_dwordx4 v[206:209], v74, s[54:55] offset:0
	global_load_dwordx4 v[210:213], v74, s[54:55] offset:16
	global_load_dwordx4 v[174:177], v66, s[52:53]
	global_load_dwordx4 v[178:181], v67, s[52:53]
	global_load_dwordx4 v[182:185], v68, s[52:53]
	global_load_dwordx4 v[186:189], v69, s[52:53]
	global_load_dwordx4 v[190:193], v70, s[52:53]
	global_load_dwordx4 v[194:197], v71, s[52:53]
	global_load_dwordx4 v[198:201], v72, s[52:53]
	global_load_dwordx4 v[202:205], v73, s[52:53]
	s_waitcnt lgkmcnt(0)
	s_barrier
	ds_read_b128 v[50:53], v76 offset:0
	ds_read_b128 v[54:57], v77 offset:8192
	ds_read_b128 v[58:61], v76 offset:16384
	ds_read_b128 v[62:65], v77 offset:24576
	s_waitcnt lgkmcnt(3)
	global_store_dwordx4 v79, v[50:53], s[68:69]
	s_waitcnt lgkmcnt(2)
	global_store_dwordx4 v80, v[54:57], s[68:69]
	s_waitcnt lgkmcnt(1)
	global_store_dwordx4 v81, v[58:61], s[68:69]
	s_waitcnt lgkmcnt(0)
	global_store_dwordx4 v82, v[62:65], s[68:69]
	s_waitcnt vmcnt(18)
	v_mul_f32_e32 v130, v130, v162
	v_mul_f32_e32 v131, v131, v162
	v_mul_f32_e32 v132, v132, v162
	v_mul_f32_e32 v133, v133, v162
	v_mul_f32_e32 v134, v134, v163
	v_mul_f32_e32 v135, v135, v163
	v_mul_f32_e32 v136, v136, v163
	v_mul_f32_e32 v137, v137, v163
	v_mul_f32_e32 v138, v138, v164
	v_mul_f32_e32 v139, v139, v164
	v_mul_f32_e32 v140, v140, v164
	v_mul_f32_e32 v141, v141, v164
	v_mul_f32_e32 v142, v142, v165
	v_mul_f32_e32 v143, v143, v165
	v_mul_f32_e32 v144, v144, v165
	v_mul_f32_e32 v145, v145, v165
	v_mul_f32_e32 v146, v146, v166
	v_mul_f32_e32 v147, v147, v166
	v_mul_f32_e32 v148, v148, v166
	v_mul_f32_e32 v149, v149, v166
	v_mul_f32_e32 v150, v150, v167
	v_mul_f32_e32 v151, v151, v167
	v_mul_f32_e32 v152, v152, v167
	v_mul_f32_e32 v153, v153, v167
	v_mul_f32_e32 v154, v154, v168
	v_mul_f32_e32 v155, v155, v168
	v_mul_f32_e32 v156, v156, v168
	v_mul_f32_e32 v157, v157, v168
	v_mul_f32_e32 v158, v158, v169
	v_mul_f32_e32 v159, v159, v169
	v_mul_f32_e32 v160, v160, v169
	v_mul_f32_e32 v161, v161, v169
	v_cvt_pk_bf16_f32 v214, v130, v134
	v_cvt_pk_bf16_f32 v215, v138, v142
	v_cvt_pk_bf16_f32 v216, v146, v150
	v_cvt_pk_bf16_f32 v217, v154, v158
	v_cvt_pk_bf16_f32 v218, v131, v135
	v_cvt_pk_bf16_f32 v219, v139, v143
	v_cvt_pk_bf16_f32 v220, v147, v151
	v_cvt_pk_bf16_f32 v221, v155, v159
	v_cvt_pk_bf16_f32 v222, v132, v136
	v_cvt_pk_bf16_f32 v223, v140, v144
	v_cvt_pk_bf16_f32 v224, v148, v152
	v_cvt_pk_bf16_f32 v225, v156, v160
	v_cvt_pk_bf16_f32 v226, v133, v137
	v_cvt_pk_bf16_f32 v227, v141, v145
	v_cvt_pk_bf16_f32 v228, v149, v153
	v_cvt_pk_bf16_f32 v229, v157, v161
	ds_write_b128 v75, v[214:217] offset:32768
	ds_write_b128 v75, v[218:221] offset:33024
	ds_write_b128 v75, v[222:225] offset:33280
	ds_write_b128 v75, v[226:229] offset:33536
	s_mov_b64 s[70:71], s[66:67]
	s_mul_i32 s12, s9, 0xba2f
	s_lshr_b32 s12, s12, 22
	s_mul_i32 s57, s12, 0x58
	s_sub_i32 s42, s9, s57
	s_mul_i32 s57, s12, 0x580000
	s_lshl_b32 s58, s42, 9
	s_add_i32 s57, s57, s58
	s_add_u32 s62, s2, s57
	s_addc_u32 s63, s3, 0
	s_lshl_b32 s58, s12, 9
	s_add_u32 s64, s4, s58
	s_addc_u32 s65, s5, 0
	s_cmp_gt_u32 s42, 43
	s_cselect_b32 s58, 0x80000, 0
	s_cselect_b32 s57, 44, 0
	s_sub_i32 s57, s42, s57
	s_lshl_b32 s57, s57, 20
	s_add_i32 s57, s57, s58
	s_lshl_b32 s58, s12, 8
	s_add_i32 s57, s57, s58
	s_add_u32 s66, s40, s57
	s_addc_u32 s67, s41, 0
	s_add_i32 s9, s9, 0x75
	s_nop 0
	global_load_dwordx4 v[162:165], v74, s[64:65] offset:0
	global_load_dwordx4 v[166:169], v74, s[64:65] offset:16
	global_load_dwordx4 v[130:133], v66, s[62:63]
	global_load_dwordx4 v[134:137], v67, s[62:63]
	global_load_dwordx4 v[138:141], v68, s[62:63]
	global_load_dwordx4 v[142:145], v69, s[62:63]
	global_load_dwordx4 v[146:149], v70, s[62:63]
	global_load_dwordx4 v[150:153], v71, s[62:63]
	global_load_dwordx4 v[154:157], v72, s[62:63]
	global_load_dwordx4 v[158:161], v73, s[62:63]
	s_waitcnt lgkmcnt(0)
	s_barrier
	ds_read_b128 v[102:105], v76 offset:32768
	ds_read_b128 v[106:109], v77 offset:40960
	ds_read_b128 v[110:113], v76 offset:49152
	ds_read_b128 v[114:117], v77 offset:57344
	s_waitcnt lgkmcnt(3)
	global_store_dwordx4 v79, v[102:105], s[70:71]
	s_waitcnt lgkmcnt(2)
	global_store_dwordx4 v80, v[106:109], s[70:71]
	s_waitcnt lgkmcnt(1)
	global_store_dwordx4 v81, v[110:113], s[70:71]
	s_waitcnt lgkmcnt(0)
	global_store_dwordx4 v82, v[114:117], s[70:71]
	s_waitcnt vmcnt(18)
	v_mul_f32_e32 v174, v174, v206
	v_mul_f32_e32 v175, v175, v206
	v_mul_f32_e32 v176, v176, v206
	v_mul_f32_e32 v177, v177, v206
	v_mul_f32_e32 v178, v178, v207
	v_mul_f32_e32 v179, v179, v207
	v_mul_f32_e32 v180, v180, v207
	v_mul_f32_e32 v181, v181, v207
	v_mul_f32_e32 v182, v182, v208
	v_mul_f32_e32 v183, v183, v208
	v_mul_f32_e32 v184, v184, v208
	v_mul_f32_e32 v185, v185, v208
	v_mul_f32_e32 v186, v186, v209
	v_mul_f32_e32 v187, v187, v209
	v_mul_f32_e32 v188, v188, v209
	v_mul_f32_e32 v189, v189, v209
	v_mul_f32_e32 v190, v190, v210
	v_mul_f32_e32 v191, v191, v210
	v_mul_f32_e32 v192, v192, v210
	v_mul_f32_e32 v193, v193, v210
	v_mul_f32_e32 v194, v194, v211
	v_mul_f32_e32 v195, v195, v211
	v_mul_f32_e32 v196, v196, v211
	v_mul_f32_e32 v197, v197, v211
	v_mul_f32_e32 v198, v198, v212
	v_mul_f32_e32 v199, v199, v212
	v_mul_f32_e32 v200, v200, v212
	v_mul_f32_e32 v201, v201, v212
	v_mul_f32_e32 v202, v202, v213
	v_mul_f32_e32 v203, v203, v213
	v_mul_f32_e32 v204, v204, v213
	v_mul_f32_e32 v205, v205, v213
	v_cvt_pk_bf16_f32 v214, v174, v178
	v_cvt_pk_bf16_f32 v215, v182, v186
	v_cvt_pk_bf16_f32 v216, v190, v194
	v_cvt_pk_bf16_f32 v217, v198, v202
	v_cvt_pk_bf16_f32 v218, v175, v179
	v_cvt_pk_bf16_f32 v219, v183, v187
	v_cvt_pk_bf16_f32 v220, v191, v195
	v_cvt_pk_bf16_f32 v221, v199, v203
	v_cvt_pk_bf16_f32 v222, v176, v180
	v_cvt_pk_bf16_f32 v223, v184, v188
	v_cvt_pk_bf16_f32 v224, v192, v196
	v_cvt_pk_bf16_f32 v225, v200, v204
	v_cvt_pk_bf16_f32 v226, v177, v181
	v_cvt_pk_bf16_f32 v227, v185, v189
	v_cvt_pk_bf16_f32 v228, v193, v197
	v_cvt_pk_bf16_f32 v229, v201, v205
	ds_write_b128 v75, v[214:217] offset:0
	ds_write_b128 v75, v[218:221] offset:256
	ds_write_b128 v75, v[222:225] offset:512
	ds_write_b128 v75, v[226:229] offset:768
	s_mov_b64 s[68:69], s[60:61]
	s_mul_i32 s12, s9, 0xba2f
	s_lshr_b32 s12, s12, 22
	s_mul_i32 s57, s12, 0x58
	s_sub_i32 s42, s9, s57
	s_mul_i32 s57, s12, 0x580000
	s_lshl_b32 s58, s42, 9
	s_add_i32 s57, s57, s58
	s_add_u32 s52, s2, s57
	s_addc_u32 s53, s3, 0
	s_lshl_b32 s58, s12, 9
	s_add_u32 s54, s4, s58
	s_addc_u32 s55, s5, 0
	s_cmp_gt_u32 s42, 43
	s_cselect_b32 s58, 0x80000, 0
	s_cselect_b32 s57, 44, 0
	s_sub_i32 s57, s42, s57
	s_lshl_b32 s57, s57, 20
	s_add_i32 s57, s57, s58
	s_lshl_b32 s58, s12, 8
	s_add_i32 s57, s57, s58
	s_add_u32 s60, s40, s57
	s_addc_u32 s61, s41, 0
	s_add_i32 s9, s9, 0x75
	s_nop 0
	global_load_dwordx4 v[206:209], v74, s[54:55] offset:0
	global_load_dwordx4 v[210:213], v74, s[54:55] offset:16
	global_load_dwordx4 v[174:177], v66, s[52:53]
	global_load_dwordx4 v[178:181], v67, s[52:53]
	global_load_dwordx4 v[182:185], v68, s[52:53]
	global_load_dwordx4 v[186:189], v69, s[52:53]
	global_load_dwordx4 v[190:193], v70, s[52:53]
	global_load_dwordx4 v[194:197], v71, s[52:53]
	global_load_dwordx4 v[198:201], v72, s[52:53]
	global_load_dwordx4 v[202:205], v73, s[52:53]
	s_waitcnt lgkmcnt(0)
	s_barrier
	ds_read_b128 v[50:53], v76 offset:0
	ds_read_b128 v[54:57], v77 offset:8192
	ds_read_b128 v[58:61], v76 offset:16384
	ds_read_b128 v[62:65], v77 offset:24576
	s_waitcnt lgkmcnt(3)
	global_store_dwordx4 v79, v[50:53], s[68:69]
	s_waitcnt lgkmcnt(2)
	global_store_dwordx4 v80, v[54:57], s[68:69]
	s_waitcnt lgkmcnt(1)
	global_store_dwordx4 v81, v[58:61], s[68:69]
	s_waitcnt lgkmcnt(0)
	global_store_dwordx4 v82, v[62:65], s[68:69]
	s_waitcnt vmcnt(18)
	v_mul_f32_e32 v130, v130, v162
	v_mul_f32_e32 v131, v131, v162
	v_mul_f32_e32 v132, v132, v162
	v_mul_f32_e32 v133, v133, v162
	v_mul_f32_e32 v134, v134, v163
	v_mul_f32_e32 v135, v135, v163
	v_mul_f32_e32 v136, v136, v163
	v_mul_f32_e32 v137, v137, v163
	v_mul_f32_e32 v138, v138, v164
	v_mul_f32_e32 v139, v139, v164
	v_mul_f32_e32 v140, v140, v164
	v_mul_f32_e32 v141, v141, v164
	v_mul_f32_e32 v142, v142, v165
	v_mul_f32_e32 v143, v143, v165
	v_mul_f32_e32 v144, v144, v165
	v_mul_f32_e32 v145, v145, v165
	v_mul_f32_e32 v146, v146, v166
	v_mul_f32_e32 v147, v147, v166
	v_mul_f32_e32 v148, v148, v166
	v_mul_f32_e32 v149, v149, v166
	v_mul_f32_e32 v150, v150, v167
	v_mul_f32_e32 v151, v151, v167
	v_mul_f32_e32 v152, v152, v167
	v_mul_f32_e32 v153, v153, v167
	v_mul_f32_e32 v154, v154, v168
	v_mul_f32_e32 v155, v155, v168
	v_mul_f32_e32 v156, v156, v168
	v_mul_f32_e32 v157, v157, v168
	v_mul_f32_e32 v158, v158, v169
	v_mul_f32_e32 v159, v159, v169
	v_mul_f32_e32 v160, v160, v169
	v_mul_f32_e32 v161, v161, v169
	v_cvt_pk_bf16_f32 v214, v130, v134
	v_cvt_pk_bf16_f32 v215, v138, v142
	v_cvt_pk_bf16_f32 v216, v146, v150
	v_cvt_pk_bf16_f32 v217, v154, v158
	v_cvt_pk_bf16_f32 v218, v131, v135
	v_cvt_pk_bf16_f32 v219, v139, v143
	v_cvt_pk_bf16_f32 v220, v147, v151
	v_cvt_pk_bf16_f32 v221, v155, v159
	v_cvt_pk_bf16_f32 v222, v132, v136
	v_cvt_pk_bf16_f32 v223, v140, v144
	v_cvt_pk_bf16_f32 v224, v148, v152
	v_cvt_pk_bf16_f32 v225, v156, v160
	v_cvt_pk_bf16_f32 v226, v133, v137
	v_cvt_pk_bf16_f32 v227, v141, v145
	v_cvt_pk_bf16_f32 v228, v149, v153
	v_cvt_pk_bf16_f32 v229, v157, v161
	ds_write_b128 v75, v[214:217] offset:32768
	ds_write_b128 v75, v[218:221] offset:33024
	ds_write_b128 v75, v[222:225] offset:33280
	ds_write_b128 v75, v[226:229] offset:33536
	s_mov_b64 s[70:71], s[66:67]
	s_mul_i32 s12, s9, 0xba2f
	s_lshr_b32 s12, s12, 22
	s_mul_i32 s57, s12, 0x58
	s_sub_i32 s42, s9, s57
	s_mul_i32 s57, s12, 0x580000
	s_lshl_b32 s58, s42, 9
	s_add_i32 s57, s57, s58
	s_add_u32 s62, s2, s57
	s_addc_u32 s63, s3, 0
	s_lshl_b32 s58, s12, 9
	s_add_u32 s64, s4, s58
	s_addc_u32 s65, s5, 0
	s_cmp_gt_u32 s42, 43
	s_cselect_b32 s58, 0x80000, 0
	s_cselect_b32 s57, 44, 0
	s_sub_i32 s57, s42, s57
	s_lshl_b32 s57, s57, 20
	s_add_i32 s57, s57, s58
	s_lshl_b32 s58, s12, 8
	s_add_i32 s57, s57, s58
	s_add_u32 s66, s40, s57
	s_addc_u32 s67, s41, 0
	s_add_i32 s9, s9, 0x75
	s_nop 0
	global_load_dwordx4 v[162:165], v74, s[64:65] offset:0
	global_load_dwordx4 v[166:169], v74, s[64:65] offset:16
	global_load_dwordx4 v[130:133], v66, s[62:63]
	global_load_dwordx4 v[134:137], v67, s[62:63]
	global_load_dwordx4 v[138:141], v68, s[62:63]
	global_load_dwordx4 v[142:145], v69, s[62:63]
	global_load_dwordx4 v[146:149], v70, s[62:63]
	global_load_dwordx4 v[150:153], v71, s[62:63]
	global_load_dwordx4 v[154:157], v72, s[62:63]
	global_load_dwordx4 v[158:161], v73, s[62:63]
	s_waitcnt lgkmcnt(0)
	s_barrier
	ds_read_b128 v[102:105], v76 offset:32768
	ds_read_b128 v[106:109], v77 offset:40960
	ds_read_b128 v[110:113], v76 offset:49152
	ds_read_b128 v[114:117], v77 offset:57344
	s_waitcnt lgkmcnt(3)
	global_store_dwordx4 v79, v[102:105], s[70:71]
	s_waitcnt lgkmcnt(2)
	global_store_dwordx4 v80, v[106:109], s[70:71]
	s_waitcnt lgkmcnt(1)
	global_store_dwordx4 v81, v[110:113], s[70:71]
	s_waitcnt lgkmcnt(0)
	global_store_dwordx4 v82, v[114:117], s[70:71]
	s_waitcnt vmcnt(18)
	v_mul_f32_e32 v174, v174, v206
	v_mul_f32_e32 v175, v175, v206
	v_mul_f32_e32 v176, v176, v206
	v_mul_f32_e32 v177, v177, v206
	v_mul_f32_e32 v178, v178, v207
	v_mul_f32_e32 v179, v179, v207
	v_mul_f32_e32 v180, v180, v207
	v_mul_f32_e32 v181, v181, v207
	v_mul_f32_e32 v182, v182, v208
	v_mul_f32_e32 v183, v183, v208
	v_mul_f32_e32 v184, v184, v208
	v_mul_f32_e32 v185, v185, v208
	v_mul_f32_e32 v186, v186, v209
	v_mul_f32_e32 v187, v187, v209
	v_mul_f32_e32 v188, v188, v209
	v_mul_f32_e32 v189, v189, v209
	v_mul_f32_e32 v190, v190, v210
	v_mul_f32_e32 v191, v191, v210
	v_mul_f32_e32 v192, v192, v210
	v_mul_f32_e32 v193, v193, v210
	v_mul_f32_e32 v194, v194, v211
	v_mul_f32_e32 v195, v195, v211
	v_mul_f32_e32 v196, v196, v211
	v_mul_f32_e32 v197, v197, v211
	v_mul_f32_e32 v198, v198, v212
	v_mul_f32_e32 v199, v199, v212
	v_mul_f32_e32 v200, v200, v212
	v_mul_f32_e32 v201, v201, v212
	v_mul_f32_e32 v202, v202, v213
	v_mul_f32_e32 v203, v203, v213
	v_mul_f32_e32 v204, v204, v213
	v_mul_f32_e32 v205, v205, v213
	v_cvt_pk_bf16_f32 v214, v174, v178
	v_cvt_pk_bf16_f32 v215, v182, v186
	v_cvt_pk_bf16_f32 v216, v190, v194
	v_cvt_pk_bf16_f32 v217, v198, v202
	v_cvt_pk_bf16_f32 v218, v175, v179
	v_cvt_pk_bf16_f32 v219, v183, v187
	v_cvt_pk_bf16_f32 v220, v191, v195
	v_cvt_pk_bf16_f32 v221, v199, v203
	v_cvt_pk_bf16_f32 v222, v176, v180
	v_cvt_pk_bf16_f32 v223, v184, v188
	v_cvt_pk_bf16_f32 v224, v192, v196
	v_cvt_pk_bf16_f32 v225, v200, v204
	v_cvt_pk_bf16_f32 v226, v177, v181
	v_cvt_pk_bf16_f32 v227, v185, v189
	v_cvt_pk_bf16_f32 v228, v193, v197
	v_cvt_pk_bf16_f32 v229, v201, v205
	ds_write_b128 v75, v[214:217] offset:0
	ds_write_b128 v75, v[218:221] offset:256
	ds_write_b128 v75, v[222:225] offset:512
	ds_write_b128 v75, v[226:229] offset:768
	s_mov_b64 s[68:69], s[60:61]
	s_mul_i32 s12, s9, 0xba2f
	s_lshr_b32 s12, s12, 22
	s_mul_i32 s57, s12, 0x58
	s_sub_i32 s42, s9, s57
	s_mul_i32 s57, s12, 0x580000
	s_lshl_b32 s58, s42, 9
	s_add_i32 s57, s57, s58
	s_add_u32 s52, s2, s57
	s_addc_u32 s53, s3, 0
	s_lshl_b32 s58, s12, 9
	s_add_u32 s54, s4, s58
	s_addc_u32 s55, s5, 0
	s_cmp_gt_u32 s42, 43
	s_cselect_b32 s58, 0x80000, 0
	s_cselect_b32 s57, 44, 0
	s_sub_i32 s57, s42, s57
	s_lshl_b32 s57, s57, 20
	s_add_i32 s57, s57, s58
	s_lshl_b32 s58, s12, 8
	s_add_i32 s57, s57, s58
	s_add_u32 s60, s40, s57
	s_addc_u32 s61, s41, 0
	s_add_i32 s9, s9, 0x75
	s_nop 0
	global_load_dwordx4 v[206:209], v74, s[54:55] offset:0
	global_load_dwordx4 v[210:213], v74, s[54:55] offset:16
	global_load_dwordx4 v[174:177], v66, s[52:53]
	global_load_dwordx4 v[178:181], v67, s[52:53]
	global_load_dwordx4 v[182:185], v68, s[52:53]
	global_load_dwordx4 v[186:189], v69, s[52:53]
	global_load_dwordx4 v[190:193], v70, s[52:53]
	global_load_dwordx4 v[194:197], v71, s[52:53]
	global_load_dwordx4 v[198:201], v72, s[52:53]
	global_load_dwordx4 v[202:205], v73, s[52:53]
	s_waitcnt lgkmcnt(0)
	s_barrier
	ds_read_b128 v[50:53], v76 offset:0
	ds_read_b128 v[54:57], v77 offset:8192
	ds_read_b128 v[58:61], v76 offset:16384
	ds_read_b128 v[62:65], v77 offset:24576
	s_waitcnt lgkmcnt(3)
	global_store_dwordx4 v79, v[50:53], s[68:69]
	s_waitcnt lgkmcnt(2)
	global_store_dwordx4 v80, v[54:57], s[68:69]
	s_waitcnt lgkmcnt(1)
	global_store_dwordx4 v81, v[58:61], s[68:69]
	s_waitcnt lgkmcnt(0)
	global_store_dwordx4 v82, v[62:65], s[68:69]
	s_waitcnt vmcnt(18)
	v_mul_f32_e32 v130, v130, v162
	v_mul_f32_e32 v131, v131, v162
	v_mul_f32_e32 v132, v132, v162
	v_mul_f32_e32 v133, v133, v162
	v_mul_f32_e32 v134, v134, v163
	v_mul_f32_e32 v135, v135, v163
	v_mul_f32_e32 v136, v136, v163
	v_mul_f32_e32 v137, v137, v163
	v_mul_f32_e32 v138, v138, v164
	v_mul_f32_e32 v139, v139, v164
	v_mul_f32_e32 v140, v140, v164
	v_mul_f32_e32 v141, v141, v164
	v_mul_f32_e32 v142, v142, v165
	v_mul_f32_e32 v143, v143, v165
	v_mul_f32_e32 v144, v144, v165
	v_mul_f32_e32 v145, v145, v165
	v_mul_f32_e32 v146, v146, v166
	v_mul_f32_e32 v147, v147, v166
	v_mul_f32_e32 v148, v148, v166
	v_mul_f32_e32 v149, v149, v166
	v_mul_f32_e32 v150, v150, v167
	v_mul_f32_e32 v151, v151, v167
	v_mul_f32_e32 v152, v152, v167
	v_mul_f32_e32 v153, v153, v167
	v_mul_f32_e32 v154, v154, v168
	v_mul_f32_e32 v155, v155, v168
	v_mul_f32_e32 v156, v156, v168
	v_mul_f32_e32 v157, v157, v168
	v_mul_f32_e32 v158, v158, v169
	v_mul_f32_e32 v159, v159, v169
	v_mul_f32_e32 v160, v160, v169
	v_mul_f32_e32 v161, v161, v169
	v_cvt_pk_bf16_f32 v214, v130, v134
	v_cvt_pk_bf16_f32 v215, v138, v142
	v_cvt_pk_bf16_f32 v216, v146, v150
	v_cvt_pk_bf16_f32 v217, v154, v158
	v_cvt_pk_bf16_f32 v218, v131, v135
	v_cvt_pk_bf16_f32 v219, v139, v143
	v_cvt_pk_bf16_f32 v220, v147, v151
	v_cvt_pk_bf16_f32 v221, v155, v159
	v_cvt_pk_bf16_f32 v222, v132, v136
	v_cvt_pk_bf16_f32 v223, v140, v144
	v_cvt_pk_bf16_f32 v224, v148, v152
	v_cvt_pk_bf16_f32 v225, v156, v160
	v_cvt_pk_bf16_f32 v226, v133, v137
	v_cvt_pk_bf16_f32 v227, v141, v145
	v_cvt_pk_bf16_f32 v228, v149, v153
	v_cvt_pk_bf16_f32 v229, v157, v161
	ds_write_b128 v75, v[214:217] offset:32768
	ds_write_b128 v75, v[218:221] offset:33024
	ds_write_b128 v75, v[222:225] offset:33280
	ds_write_b128 v75, v[226:229] offset:33536
	s_mov_b64 s[70:71], s[66:67]
	s_mul_i32 s12, s9, 0xba2f
	s_lshr_b32 s12, s12, 22
	s_mul_i32 s57, s12, 0x58
	s_sub_i32 s42, s9, s57
	s_mul_i32 s57, s12, 0x580000
	s_lshl_b32 s58, s42, 9
	s_add_i32 s57, s57, s58
	s_add_u32 s62, s2, s57
	s_addc_u32 s63, s3, 0
	s_lshl_b32 s58, s12, 9
	s_add_u32 s64, s4, s58
	s_addc_u32 s65, s5, 0
	s_cmp_gt_u32 s42, 43
	s_cselect_b32 s58, 0x80000, 0
	s_cselect_b32 s57, 44, 0
	s_sub_i32 s57, s42, s57
	s_lshl_b32 s57, s57, 20
	s_add_i32 s57, s57, s58
	s_lshl_b32 s58, s12, 8
	s_add_i32 s57, s57, s58
	s_add_u32 s66, s40, s57
	s_addc_u32 s67, s41, 0
	s_add_i32 s9, s9, 0x75
	s_nop 0
	global_load_dwordx4 v[162:165], v74, s[64:65] offset:0
	global_load_dwordx4 v[166:169], v74, s[64:65] offset:16
	global_load_dwordx4 v[130:133], v66, s[62:63]
	global_load_dwordx4 v[134:137], v67, s[62:63]
	global_load_dwordx4 v[138:141], v68, s[62:63]
	global_load_dwordx4 v[142:145], v69, s[62:63]
	global_load_dwordx4 v[146:149], v70, s[62:63]
	global_load_dwordx4 v[150:153], v71, s[62:63]
	global_load_dwordx4 v[154:157], v72, s[62:63]
	global_load_dwordx4 v[158:161], v73, s[62:63]
	s_waitcnt lgkmcnt(0)
	s_barrier
	ds_read_b128 v[102:105], v76 offset:32768
	ds_read_b128 v[106:109], v77 offset:40960
	ds_read_b128 v[110:113], v76 offset:49152
	ds_read_b128 v[114:117], v77 offset:57344
	s_waitcnt lgkmcnt(3)
	global_store_dwordx4 v79, v[102:105], s[70:71]
	s_waitcnt lgkmcnt(2)
	global_store_dwordx4 v80, v[106:109], s[70:71]
	s_waitcnt lgkmcnt(1)
	global_store_dwordx4 v81, v[110:113], s[70:71]
	s_waitcnt lgkmcnt(0)
	global_store_dwordx4 v82, v[114:117], s[70:71]
	s_waitcnt vmcnt(18)
	v_mul_f32_e32 v174, v174, v206
	v_mul_f32_e32 v175, v175, v206
	v_mul_f32_e32 v176, v176, v206
	v_mul_f32_e32 v177, v177, v206
	v_mul_f32_e32 v178, v178, v207
	v_mul_f32_e32 v179, v179, v207
	v_mul_f32_e32 v180, v180, v207
	v_mul_f32_e32 v181, v181, v207
	v_mul_f32_e32 v182, v182, v208
	v_mul_f32_e32 v183, v183, v208
	v_mul_f32_e32 v184, v184, v208
	v_mul_f32_e32 v185, v185, v208
	v_mul_f32_e32 v186, v186, v209
	v_mul_f32_e32 v187, v187, v209
	v_mul_f32_e32 v188, v188, v209
	v_mul_f32_e32 v189, v189, v209
	v_mul_f32_e32 v190, v190, v210
	v_mul_f32_e32 v191, v191, v210
	v_mul_f32_e32 v192, v192, v210
	v_mul_f32_e32 v193, v193, v210
	v_mul_f32_e32 v194, v194, v211
	v_mul_f32_e32 v195, v195, v211
	v_mul_f32_e32 v196, v196, v211
	v_mul_f32_e32 v197, v197, v211
	v_mul_f32_e32 v198, v198, v212
	v_mul_f32_e32 v199, v199, v212
	v_mul_f32_e32 v200, v200, v212
	v_mul_f32_e32 v201, v201, v212
	v_mul_f32_e32 v202, v202, v213
	v_mul_f32_e32 v203, v203, v213
	v_mul_f32_e32 v204, v204, v213
	v_mul_f32_e32 v205, v205, v213
	v_cvt_pk_bf16_f32 v214, v174, v178
	v_cvt_pk_bf16_f32 v215, v182, v186
	v_cvt_pk_bf16_f32 v216, v190, v194
	v_cvt_pk_bf16_f32 v217, v198, v202
	v_cvt_pk_bf16_f32 v218, v175, v179
	v_cvt_pk_bf16_f32 v219, v183, v187
	v_cvt_pk_bf16_f32 v220, v191, v195
	v_cvt_pk_bf16_f32 v221, v199, v203
	v_cvt_pk_bf16_f32 v222, v176, v180
	v_cvt_pk_bf16_f32 v223, v184, v188
	v_cvt_pk_bf16_f32 v224, v192, v196
	v_cvt_pk_bf16_f32 v225, v200, v204
	v_cvt_pk_bf16_f32 v226, v177, v181
	v_cvt_pk_bf16_f32 v227, v185, v189
	v_cvt_pk_bf16_f32 v228, v193, v197
	v_cvt_pk_bf16_f32 v229, v201, v205
	ds_write_b128 v75, v[214:217] offset:0
	ds_write_b128 v75, v[218:221] offset:256
	ds_write_b128 v75, v[222:225] offset:512
	ds_write_b128 v75, v[226:229] offset:768
	s_mov_b64 s[68:69], s[60:61]
	s_waitcnt lgkmcnt(0)
	s_barrier
	ds_read_b128 v[50:53], v76 offset:0
	ds_read_b128 v[54:57], v77 offset:8192
	ds_read_b128 v[58:61], v76 offset:16384
	ds_read_b128 v[62:65], v77 offset:24576
	s_waitcnt lgkmcnt(3)
	global_store_dwordx4 v79, v[50:53], s[68:69]
	s_waitcnt lgkmcnt(2)
	global_store_dwordx4 v80, v[54:57], s[68:69]
	s_waitcnt lgkmcnt(1)
	global_store_dwordx4 v81, v[58:61], s[68:69]
	s_waitcnt lgkmcnt(0)
	global_store_dwordx4 v82, v[62:65], s[68:69]
	s_waitcnt vmcnt(8)
	v_mul_f32_e32 v130, v130, v162
	v_mul_f32_e32 v131, v131, v162
	v_mul_f32_e32 v132, v132, v162
	v_mul_f32_e32 v133, v133, v162
	v_mul_f32_e32 v134, v134, v163
	v_mul_f32_e32 v135, v135, v163
	v_mul_f32_e32 v136, v136, v163
	v_mul_f32_e32 v137, v137, v163
	v_mul_f32_e32 v138, v138, v164
	v_mul_f32_e32 v139, v139, v164
	v_mul_f32_e32 v140, v140, v164
	v_mul_f32_e32 v141, v141, v164
	v_mul_f32_e32 v142, v142, v165
	v_mul_f32_e32 v143, v143, v165
	v_mul_f32_e32 v144, v144, v165
	v_mul_f32_e32 v145, v145, v165
	v_mul_f32_e32 v146, v146, v166
	v_mul_f32_e32 v147, v147, v166
	v_mul_f32_e32 v148, v148, v166
	v_mul_f32_e32 v149, v149, v166
	v_mul_f32_e32 v150, v150, v167
	v_mul_f32_e32 v151, v151, v167
	v_mul_f32_e32 v152, v152, v167
	v_mul_f32_e32 v153, v153, v167
	v_mul_f32_e32 v154, v154, v168
	v_mul_f32_e32 v155, v155, v168
	v_mul_f32_e32 v156, v156, v168
	v_mul_f32_e32 v157, v157, v168
	v_mul_f32_e32 v158, v158, v169
	v_mul_f32_e32 v159, v159, v169
	v_mul_f32_e32 v160, v160, v169
	v_mul_f32_e32 v161, v161, v169
	v_cvt_pk_bf16_f32 v214, v130, v134
	v_cvt_pk_bf16_f32 v215, v138, v142
	v_cvt_pk_bf16_f32 v216, v146, v150
	v_cvt_pk_bf16_f32 v217, v154, v158
	v_cvt_pk_bf16_f32 v218, v131, v135
	v_cvt_pk_bf16_f32 v219, v139, v143
	v_cvt_pk_bf16_f32 v220, v147, v151
	v_cvt_pk_bf16_f32 v221, v155, v159
	v_cvt_pk_bf16_f32 v222, v132, v136
	v_cvt_pk_bf16_f32 v223, v140, v144
	v_cvt_pk_bf16_f32 v224, v148, v152
	v_cvt_pk_bf16_f32 v225, v156, v160
	v_cvt_pk_bf16_f32 v226, v133, v137
	v_cvt_pk_bf16_f32 v227, v141, v145
	v_cvt_pk_bf16_f32 v228, v149, v153
	v_cvt_pk_bf16_f32 v229, v157, v161
	ds_write_b128 v75, v[214:217] offset:32768
	ds_write_b128 v75, v[218:221] offset:33024
	ds_write_b128 v75, v[222:225] offset:33280
	ds_write_b128 v75, v[226:229] offset:33536
	s_mov_b64 s[70:71], s[66:67]
	s_waitcnt lgkmcnt(0)
	s_barrier
	ds_read_b128 v[102:105], v76 offset:32768
	ds_read_b128 v[106:109], v77 offset:40960
	ds_read_b128 v[110:113], v76 offset:49152
	ds_read_b128 v[114:117], v77 offset:57344
	s_waitcnt lgkmcnt(3)
	global_store_dwordx4 v79, v[102:105], s[70:71]
	s_waitcnt lgkmcnt(2)
	global_store_dwordx4 v80, v[106:109], s[70:71]
	s_waitcnt lgkmcnt(1)
	global_store_dwordx4 v81, v[110:113], s[70:71]
	s_waitcnt lgkmcnt(0)
	global_store_dwordx4 v82, v[114:117], s[70:71]
	s_waitcnt vmcnt(0)
	s_barrier

.LBB0_776:
	s_cmpk_lg_i32 s96, 0x100
	s_cselect_b64 s[0:1], -1, 0
	s_cmpk_lt_i32 s76, 0x42
	s_cselect_b64 s[2:3], -1, 0
	s_or_b64 s[0:1], s[2:3], s[0:1]
	s_and_b64 vcc, exec, s[0:1]
	s_cbranch_vccnz .LBB0_830
	s_cmpk_lt_u32 s76, 0x302
	v_mov_b32_e32 v35, v172
	s_cselect_b64 s[10:11], -1, 0
	s_and_b64 vcc, exec, s[10:11]
	v_ashrrev_i32_e32 v32, 5, v35
	v_lshlrev_b32_e32 v0, 2, v35
	s_cbranch_vccnz .LBB0_780
	v_ashrrev_i32_e32 v33, 5, v35
	v_and_b32_e32 v39, 0x7c, v0
	s_cbranch_execz .LBB0_781
	v_mov_b32_e32 v31, 0
	v_mov_b32_e32 v30, v31
	v_mov_b32_e32 v29, v31
	v_mov_b32_e32 v28, v31
	v_mov_b32_e32 v27, v31
	v_mov_b32_e32 v26, v31
	v_mov_b32_e32 v25, v31
	v_mov_b32_e32 v24, v31
	v_mov_b32_e32 v23, v31
	v_mov_b32_e32 v22, v31
	v_mov_b32_e32 v21, v31
	v_mov_b32_e32 v20, v31
	v_mov_b32_e32 v19, v31
	v_mov_b32_e32 v18, v31
	v_mov_b32_e32 v17, v31
	v_mov_b32_e32 v16, v31
	v_mov_b32_e32 v15, v31
	v_mov_b32_e32 v14, v31
	v_mov_b32_e32 v13, v31
	v_mov_b32_e32 v12, v31
	v_mov_b32_e32 v11, v31
	v_mov_b32_e32 v10, v31
	v_mov_b32_e32 v9, v31
	v_mov_b32_e32 v8, v31
	v_mov_b32_e32 v7, v31
	v_mov_b32_e32 v6, v31
	v_mov_b32_e32 v5, v31
	v_mov_b32_e32 v4, v31
	s_waitcnt lgkmcnt(0)
	v_mov_b32_e32 v3, v31
	v_mov_b32_e32 v2, v31
	v_mov_b32_e32 v1, v31
	v_mov_b32_e32 v0, v31
	v_mov_b32_e32 v32, v33
	s_andn2_b64 vcc, exec, s[10:11]
	s_cbranch_vccz .LBB0_803
	s_branch .LBB0_829
.LBB0_780:
.LBB0_781:
	s_add_i32 s9, s76, 0xb0e
	s_cmpk_gt_u32 s76, 0x41
	s_cbranch_scc0 .LBB0_784
	s_add_u32 s6, s92, 0x5c00000
	s_addc_u32 s7, s93, 0
	s_lshl_b32 s0, s9, 3
	s_and_b32 s0, s0, 0xff80
	s_add_i32 s8, s0, 0xffffa580
	s_lshl_b32 s0, s9, 7
	s_and_b32 s12, s0, 0x780
	s_mov_b64 s[0:1], s[52:53]
	s_mov_b64 s[14:15], 0
	s_cbranch_execz .LBB0_785
	s_movk_i32 s2, 0x800
	s_movk_i32 s28, 0x1600
	s_mov_b32 s29, s12
	s_branch .LBB0_786

.LBB0_803:
	s_add_u32 s10, s92, 0x5c00000
	s_addc_u32 s11, s93, 0
	s_movk_i32 s0, 0x204
	s_add_u32 s12, s92, 0x3000000
	v_ashrrev_i32_e32 v41, 4, v35
	v_lshlrev_b32_e32 v35, 3, v35
	v_mul_lo_u32 v45, v32, s0
	s_addc_u32 s13, s93, 0
	s_lshl_b32 s0, s76, 7
	v_and_b32_e32 v50, 0x78, v35
	s_add_i32 s31, s0, 0x5e600
	s_lshl_b32 s0, s76, 3
	v_ashrrev_i32_e32 v33, 31, v32
	v_mul_u32_u24_e32 v43, 0x204, v50
	v_mov_b32_e32 v35, 0
	s_add_i32 s30, s76, 0xbcc
	s_add_i32 s33, s0, 0x5e60
	s_mov_b32 s34, 0
	v_lshlrev_b32_e32 v47, 2, v39
	v_lshlrev_b32_e32 v50, 1, v50
	s_branch .LBB0_806
